# attention: static s_setprio 1 for waves 0-3 (older half) experiment
# speedup vs baseline: 1.0007x; 1.0007x over previous
.LBB0_135:
	v_readlane_b32 s0, v249, 27
	s_nop 3
	s_cmpk_gt_u32 s0, 0xff
	s_cbranch_scc1 .Lattn_prio_done
	s_setprio 1
